# serial chain: LDS operand reads software-pipelined one step ahead (two register sets), U-MFMAs first, barrier off the recurrence path; no duplicate DMAs
# speedup vs baseline: 1.0169x; 1.0169x over previous
.LBB0_406:
	v_and_b32_e32 v1, 63, v0
	v_and_b32_e32 v2, 15, v1
	v_lshrrev_b32_e32 v3, 4, v1
	v_readfirstlane_b32 s6, v0
	s_lshr_b32 s7, s2, 4
	s_and_b32 s8, s2, 15
	s_nop 0
	s_lshr_b32 s6, s6, 6
	s_cmp_gt_u32 s6, 3
	s_cbranch_scc1 .Lser_loader
	v_lshrrev_b32_e32 v4, 1, v3
	v_and_b32_e32 v5, 1, v3
	v_lshlrev_b32_e32 v4, 8, v4
	v_lshl_add_u32 v4, v2, 4, v4
	v_lshl_add_u32 v4, v5, 3, v4
	s_lshl_b32 s12, s6, 4
	v_add_u32_e32 v5, s12, v2
	v_lshlrev_b32_e32 v6, 5, v5
	v_lshl_add_u32 v6, v3, 3, v6
	v_add_u32_e32 v6, 0x2400, v6
	v_lshlrev_b32_e32 v7, 9, v3
	v_lshl_add_u32 v7, v5, 1, v7
	v_add_u32_e32 v7, 0x2c00, v7
	v_lshlrev_b32_e32 v120, 4, v3
	v_add_u32_e32 v120, 0x3400, v120
	v_lshlrev_b32_e32 v116, 13, v3
	v_lshl_add_u32 v116, v5, 1, v116
	s_lshl_b32 s12, s7, 23
	s_lshl_b32 s13, s8, 7
	s_add_u32 s12, s12, s13
	s_add_u32 s12, s12, 0x14a08000
	v_add_u32_e32 v116, s12, v116
	v_mov_b32_e32 v117, 0
	s_mov_b64 s[14:15], 0x1000
	s_mov_b64 s[16:17], 0x8000
	v_lshl_add_u64 v[116:117], v[116:117], 0, s[70:71]
	v_lshl_add_u64 v[118:119], v[116:117], 0, s[14:15]
	v_mov_b32_e32 v8, 0
	v_mov_b32_e32 v9, 0
	v_mov_b32_e32 v10, 0
	v_mov_b32_e32 v11, 0
	v_mov_b32_e32 v12, 0
	v_mov_b32_e32 v13, 0
	v_mov_b32_e32 v14, 0
	v_mov_b32_e32 v15, 0
	v_mov_b32_e32 v16, 0
	v_mov_b32_e32 v17, 0
	v_mov_b32_e32 v18, 0
	v_mov_b32_e32 v19, 0
	v_mov_b32_e32 v20, 0
	v_mov_b32_e32 v21, 0
	v_mov_b32_e32 v22, 0
	v_mov_b32_e32 v23, 0
	v_mov_b32_e32 v24, 0
	v_mov_b32_e32 v25, 0
	v_mov_b32_e32 v26, 0
	v_mov_b32_e32 v27, 0
	v_mov_b32_e32 v28, 0
	v_mov_b32_e32 v29, 0
	v_mov_b32_e32 v30, 0
	v_mov_b32_e32 v31, 0
	s_mov_b32 s10, 0
	s_mov_b32 s11, 0
	s_barrier
	v_add_u32_e32 v121, s10, v4
	v_add_u32_e32 v126, s10, v6
	v_add_u32_e32 v127, s10, v7
	v_add_u32_e32 v128, s10, v120
	v_add_u32_e32 v122, 0x800, v121
	v_add_u32_e32 v123, 0x1000, v121
	v_add_u32_e32 v124, 0x1800, v121
	v_add_u32_e32 v125, 0x2000, v121
	ds_read_b64 v[48:49], v126
	ds_read2_b64 v[32:35], v121 offset1:64
	ds_read2_b64 v[36:39], v121 offset0:128 offset1:192
	ds_read2_b64 v[40:43], v122 offset1:64
	ds_read2_b64 v[44:47], v122 offset0:128 offset1:192
	ds_read_b128 v[82:85], v128
	ds_read_b128 v[86:89], v128 offset:64
	ds_read_b128 v[90:93], v128 offset:128
	ds_read_b128 v[94:97], v128 offset:192
	ds_read_u16 v133, v127
	ds_read_u16 v134, v127 offset:128
	ds_read_u16 v135, v127 offset:256
	ds_read_u16 v136, v127 offset:384
	ds_read2_b64 v[62:65], v123 offset1:64
	ds_read2_b64 v[66:69], v123 offset0:128 offset1:192
	ds_read2_b64 v[70:73], v124 offset1:64
	ds_read2_b64 v[74:77], v124 offset0:128 offset1:192
	ds_read2_b64 v[78:81], v125 offset1:64
	s_add_u32 s10, s10, 0x3800
	s_cmp_eq_u32 s10, 0x1c000
	s_cselect_b32 s10, 0, s10
	s_waitcnt lgkmcnt(0)
	v_lshl_or_b32 v60, v134, 16, v133
	v_lshl_or_b32 v61, v136, 16, v135
	v_lshlrev_b32_e32 v50, 16, v48
	v_and_b32_e32 v51, 0xffff0000, v48
	v_lshlrev_b32_e32 v52, 16, v49
	v_and_b32_e32 v53, 0xffff0000, v49
.Lser_chain_loop:
	s_nop 1
	v_mfma_f32_16x16x32_bf16 v[50:53], v[32:35], v[24:27], v[50:53]
	v_mfma_f32_16x16x32_bf16 v[50:53], v[36:39], v[28:31], v[50:53]
	s_barrier
	v_mfma_f32_16x16x32_bf16 v[54:57], v[40:43], v[24:27], 0
	v_mfma_f32_16x16x32_bf16 v[54:57], v[44:47], v[28:31], v[54:57]
	v_pk_mul_f32 v[98:99], v[8:9], v[82:83]
	v_pk_mul_f32 v[100:101], v[10:11], v[84:85]
	v_pk_mul_f32 v[102:103], v[12:13], v[86:87]
	v_pk_mul_f32 v[104:105], v[14:15], v[88:89]
	v_pk_mul_f32 v[106:107], v[16:17], v[90:91]
	v_pk_mul_f32 v[108:109], v[18:19], v[92:93]
	v_pk_mul_f32 v[110:111], v[20:21], v[94:95]
	v_pk_mul_f32 v[112:113], v[22:23], v[96:97]
	v_cvt_pk_bf16_f32 v58, v50, v51
	v_cvt_pk_bf16_f32 v59, v52, v53
	s_nop 1
	v_mfma_f32_16x16x32_bf16 v[8:11], v[62:65], v[58:61], v[98:101]
	v_mfma_f32_16x16x32_bf16 v[12:15], v[66:69], v[58:61], v[102:105]
	v_mfma_f32_16x16x32_bf16 v[16:19], v[70:73], v[58:61], v[106:109]
	v_mfma_f32_16x16x32_bf16 v[20:23], v[74:77], v[58:61], v[110:113]
	v_mfma_f32_16x16x32_bf16 v[54:57], v[78:81], v[58:61], v[54:57]
	v_add_u32_e32 v121, s10, v4
	v_add_u32_e32 v126, s10, v6
	v_add_u32_e32 v127, s10, v7
	v_add_u32_e32 v128, s10, v120
	v_add_u32_e32 v122, 0x800, v121
	v_add_u32_e32 v123, 0x1000, v121
	v_add_u32_e32 v124, 0x1800, v121
	v_add_u32_e32 v125, 0x2000, v121
	ds_read_b64 v[140:141], v126
	ds_read2_b64 v[142:145], v121 offset1:64
	ds_read2_b64 v[146:149], v121 offset0:128 offset1:192
	ds_read2_b64 v[150:153], v122 offset1:64
	ds_read2_b64 v[154:157], v122 offset0:128 offset1:192
	ds_read_b128 v[158:161], v128
	ds_read_b128 v[162:165], v128 offset:64
	ds_read_b128 v[166:169], v128 offset:128
	ds_read_b128 v[170:173], v128 offset:192
	ds_read_u16 v174, v127
	ds_read_u16 v175, v127 offset:128
	ds_read_u16 v176, v127 offset:256
	ds_read_u16 v177, v127 offset:384
	ds_read2_b64 v[184:187], v123 offset1:64
	ds_read2_b64 v[188:191], v123 offset0:128 offset1:192
	ds_read2_b64 v[192:195], v124 offset1:64
	ds_read2_b64 v[196:199], v124 offset0:128 offset1:192
	ds_read2_b64 v[200:203], v125 offset1:64
	s_add_u32 s10, s10, 0x3800
	s_cmp_eq_u32 s10, 0x1c000
	s_cselect_b32 s10, 0, s10
	v_cvt_pk_bf16_f32 v24, v8, v9
	v_cvt_pk_bf16_f32 v25, v10, v11
	v_cvt_pk_bf16_f32 v26, v12, v13
	v_cvt_pk_bf16_f32 v27, v14, v15
	v_cvt_pk_bf16_f32 v28, v16, v17
	v_cvt_pk_bf16_f32 v29, v18, v19
	v_cvt_pk_bf16_f32 v30, v20, v21
	v_cvt_pk_bf16_f32 v31, v22, v23
	v_cvt_pk_bf16_f32 v114, v54, v54
	v_cvt_pk_bf16_f32 v115, v55, v55
	v_cvt_pk_bf16_f32 v131, v56, v56
	v_cvt_pk_bf16_f32 v132, v57, v57
	global_store_short v[116:117], v114, off
	global_store_short v[116:117], v115, off offset:2048
	global_store_short v[118:119], v131, off
	global_store_short v[118:119], v132, off offset:2048
	v_lshl_add_u64 v[116:117], v[116:117], 0, s[16:17]
	v_lshl_add_u64 v[118:119], v[118:119], 0, s[16:17]
	s_waitcnt lgkmcnt(0)
	v_lshl_or_b32 v182, v175, 16, v174
	v_lshl_or_b32 v183, v177, 16, v176
	v_lshlrev_b32_e32 v50, 16, v140
	v_and_b32_e32 v51, 0xffff0000, v140
	v_lshlrev_b32_e32 v52, 16, v141
	v_and_b32_e32 v53, 0xffff0000, v141
	s_nop 1
	v_mfma_f32_16x16x32_bf16 v[50:53], v[142:145], v[24:27], v[50:53]
	v_mfma_f32_16x16x32_bf16 v[50:53], v[146:149], v[28:31], v[50:53]
	s_barrier
	v_mfma_f32_16x16x32_bf16 v[54:57], v[150:153], v[24:27], 0
	v_mfma_f32_16x16x32_bf16 v[54:57], v[154:157], v[28:31], v[54:57]
	v_pk_mul_f32 v[98:99], v[8:9], v[158:159]
	v_pk_mul_f32 v[100:101], v[10:11], v[160:161]
	v_pk_mul_f32 v[102:103], v[12:13], v[162:163]
	v_pk_mul_f32 v[104:105], v[14:15], v[164:165]
	v_pk_mul_f32 v[106:107], v[16:17], v[166:167]
	v_pk_mul_f32 v[108:109], v[18:19], v[168:169]
	v_pk_mul_f32 v[110:111], v[20:21], v[170:171]
	v_pk_mul_f32 v[112:113], v[22:23], v[172:173]
	v_cvt_pk_bf16_f32 v180, v50, v51
	v_cvt_pk_bf16_f32 v181, v52, v53
	s_nop 1
	v_mfma_f32_16x16x32_bf16 v[8:11], v[184:187], v[180:183], v[98:101]
	v_mfma_f32_16x16x32_bf16 v[12:15], v[188:191], v[180:183], v[102:105]
	v_mfma_f32_16x16x32_bf16 v[16:19], v[192:195], v[180:183], v[106:109]
	v_mfma_f32_16x16x32_bf16 v[20:23], v[196:199], v[180:183], v[110:113]
	v_mfma_f32_16x16x32_bf16 v[54:57], v[200:203], v[180:183], v[54:57]
	v_add_u32_e32 v121, s10, v4
	v_add_u32_e32 v126, s10, v6
	v_add_u32_e32 v127, s10, v7
	v_add_u32_e32 v128, s10, v120
	v_add_u32_e32 v122, 0x800, v121
	v_add_u32_e32 v123, 0x1000, v121
	v_add_u32_e32 v124, 0x1800, v121
	v_add_u32_e32 v125, 0x2000, v121
	ds_read_b64 v[48:49], v126
	ds_read2_b64 v[32:35], v121 offset1:64
	ds_read2_b64 v[36:39], v121 offset0:128 offset1:192
	ds_read2_b64 v[40:43], v122 offset1:64
	ds_read2_b64 v[44:47], v122 offset0:128 offset1:192
	ds_read_b128 v[82:85], v128
	ds_read_b128 v[86:89], v128 offset:64
	ds_read_b128 v[90:93], v128 offset:128
	ds_read_b128 v[94:97], v128 offset:192
	ds_read_u16 v133, v127
	ds_read_u16 v134, v127 offset:128
	ds_read_u16 v135, v127 offset:256
	ds_read_u16 v136, v127 offset:384
	ds_read2_b64 v[62:65], v123 offset1:64
	ds_read2_b64 v[66:69], v123 offset0:128 offset1:192
	ds_read2_b64 v[70:73], v124 offset1:64
	ds_read2_b64 v[74:77], v124 offset0:128 offset1:192
	ds_read2_b64 v[78:81], v125 offset1:64
	s_add_u32 s10, s10, 0x3800
	s_cmp_eq_u32 s10, 0x1c000
	s_cselect_b32 s10, 0, s10
	v_cvt_pk_bf16_f32 v24, v8, v9
	v_cvt_pk_bf16_f32 v25, v10, v11
	v_cvt_pk_bf16_f32 v26, v12, v13
	v_cvt_pk_bf16_f32 v27, v14, v15
	v_cvt_pk_bf16_f32 v28, v16, v17
	v_cvt_pk_bf16_f32 v29, v18, v19
	v_cvt_pk_bf16_f32 v30, v20, v21
	v_cvt_pk_bf16_f32 v31, v22, v23
	v_cvt_pk_bf16_f32 v114, v54, v54
	v_cvt_pk_bf16_f32 v115, v55, v55
	v_cvt_pk_bf16_f32 v131, v56, v56
	v_cvt_pk_bf16_f32 v132, v57, v57
	global_store_short v[116:117], v114, off
	global_store_short v[116:117], v115, off offset:2048
	global_store_short v[118:119], v131, off
	global_store_short v[118:119], v132, off offset:2048
	v_lshl_add_u64 v[116:117], v[116:117], 0, s[16:17]
	v_lshl_add_u64 v[118:119], v[118:119], 0, s[16:17]
	s_waitcnt lgkmcnt(0)
	v_lshl_or_b32 v60, v134, 16, v133
	v_lshl_or_b32 v61, v136, 16, v135
	v_lshlrev_b32_e32 v50, 16, v48
	v_and_b32_e32 v51, 0xffff0000, v48
	v_lshlrev_b32_e32 v52, 16, v49
	v_and_b32_e32 v53, 0xffff0000, v49
	s_add_u32 s11, s11, 2
	s_cmp_lt_u32 s11, 0x100
	s_cbranch_scc1 .Lser_chain_loop
	s_branch .Lser_exit

.Lser_ld_go:
	s_mov_b32 s28, 0
	s_mov_b32 s29, 0
	s_cmp_eq_u32 s9, 3
	s_cbranch_scc1 .Lser_ld3_pro
.Lser_ld_pro:
	s_cmp_lt_u32 s29, 0xff
	s_cselect_b32 s72, s20, 0
	s_cselect_b32 s73, s21, 0
	s_cselect_b32 s74, s22, 0
	s_cselect_b32 s75, s23, 0
	s_add_u32 m0, s28, s24
	s_nop 0
	global_load_lds_dwordx4 v10, s[12:13]
	s_add_u32 s12, s12, s72
	s_addc_u32 s13, s13, 0
	s_add_u32 m0, s28, s25
	s_nop 0
	global_load_lds_dwordx4 v11, s[14:15]
	s_add_u32 s14, s14, s73
	s_addc_u32 s15, s15, 0
	s_add_u32 m0, s28, s26
	s_nop 0
	global_load_lds_dwordx4 v12, s[16:17]
	s_add_u32 s16, s16, s74
	s_addc_u32 s17, s17, 0
	s_add_u32 m0, s28, s27
	s_nop 0
	global_load_lds_dwordx4 v13, s[18:19]
	s_add_u32 s18, s18, s75
	s_addc_u32 s19, s19, 0
	s_add_u32 s28, s28, 0x3800
	s_cmp_eq_u32 s28, 0x1c000
	s_cselect_b32 s28, 0, s28
	s_add_u32 s29, s29, 1
	s_cmp_lt_u32 s29, 7
	s_cbranch_scc1 .Lser_ld_pro
	s_waitcnt vmcnt(24)
	s_barrier
	s_mov_b32 s3, 0
.Lser_ld_loop:
	s_waitcnt vmcnt(20)
	s_barrier
	s_cmp_lt_u32 s29, 0xff
	s_cselect_b32 s72, s20, 0
	s_cselect_b32 s73, s21, 0
	s_cselect_b32 s74, s22, 0
	s_cselect_b32 s75, s23, 0
	s_add_u32 m0, s28, s24
	s_nop 0
	global_load_lds_dwordx4 v10, s[12:13]
	s_add_u32 s12, s12, s72
	s_addc_u32 s13, s13, 0
	s_add_u32 m0, s28, s25
	s_nop 0
	global_load_lds_dwordx4 v11, s[14:15]
	s_add_u32 s14, s14, s73
	s_addc_u32 s15, s15, 0
	s_add_u32 m0, s28, s26
	s_nop 0
	global_load_lds_dwordx4 v12, s[16:17]
	s_add_u32 s16, s16, s74
	s_addc_u32 s17, s17, 0
	s_add_u32 m0, s28, s27
	s_nop 0
	global_load_lds_dwordx4 v13, s[18:19]
	s_add_u32 s18, s18, s75
	s_addc_u32 s19, s19, 0
	s_add_u32 s28, s28, 0x3800
	s_cmp_eq_u32 s28, 0x1c000
	s_cselect_b32 s28, 0, s28
	s_add_u32 s29, s29, 1
	s_add_u32 s3, s3, 1
	s_cmp_lt_u32 s3, 0x100
	s_cbranch_scc1 .Lser_ld_loop
	s_waitcnt vmcnt(0)
	s_branch .Lser_exit
.Lser_ld3_pro:
	s_cmp_lt_u32 s29, 0xff
	s_cselect_b32 s72, s20, 0
	s_cselect_b32 s73, s21, 0
	s_add_u32 m0, s28, s24
	s_nop 0
	global_load_lds_dwordx4 v10, s[12:13]
	s_add_u32 s12, s12, s72
	s_addc_u32 s13, s13, 0
	s_add_u32 m0, s28, s25
	s_nop 0
	global_load_lds_dwordx4 v11, s[14:15]
	s_add_u32 s14, s14, s73
	s_addc_u32 s15, s15, 0
	s_add_u32 s28, s28, 0x3800
	s_cmp_eq_u32 s28, 0x1c000
	s_cselect_b32 s28, 0, s28
	s_add_u32 s29, s29, 1
	s_cmp_lt_u32 s29, 7
	s_cbranch_scc1 .Lser_ld3_pro
	s_waitcnt vmcnt(12)
	s_barrier
	s_mov_b32 s3, 0
.Lser_ld3_loop:
	s_waitcnt vmcnt(10)
	s_barrier
	s_cmp_lt_u32 s29, 0xff
	s_cselect_b32 s72, s20, 0
	s_cselect_b32 s73, s21, 0
	s_add_u32 m0, s28, s24
	s_nop 0
	global_load_lds_dwordx4 v10, s[12:13]
	s_add_u32 s12, s12, s72
	s_addc_u32 s13, s13, 0
	s_add_u32 m0, s28, s25
	s_nop 0
	global_load_lds_dwordx4 v11, s[14:15]
	s_add_u32 s14, s14, s73
	s_addc_u32 s15, s15, 0
	s_add_u32 s28, s28, 0x3800
	s_cmp_eq_u32 s28, 0x1c000
	s_cselect_b32 s28, 0, s28
	s_add_u32 s29, s29, 1
	s_add_u32 s3, s3, 1
	s_cmp_lt_u32 s3, 0x100
	s_cbranch_scc1 .Lser_ld3_loop
	s_waitcnt vmcnt(0)
